# v_n1 + attention LDS-DMA pieces issued after the next V-fragment reads (one step later than v_d1)
# baseline (speedup 1.0000x reference)
.LBB0_1011:
	s_nop 3
	v_exp_f32_e32 v96, v96
	v_exp_f32_e32 v97, v97
	v_exp_f32_e32 v98, v98
	v_exp_f32_e32 v99, v99
	v_exp_f32_e32 v100, v100
	v_exp_f32_e32 v101, v101
	v_exp_f32_e32 v102, v102
	v_exp_f32_e32 v103, v103
	v_cvt_pk_bf16_f32 v216, v96, v97
	v_cvt_pk_bf16_f32 v217, v98, v99
	v_cvt_pk_bf16_f32 v218, v100, v101
	v_cvt_pk_bf16_f32 v219, v102, v103
	ds_read_b64_tr_b16 v[152:153], v156 offset:17408
	ds_read_b64_tr_b16 v[154:155], v156 offset:17920
	ds_read_b64_tr_b16 v[148:149], v156 offset:21504
	ds_read_b64_tr_b16 v[150:151], v156 offset:22016
	ds_read_b64_tr_b16 v[100:101], v156 offset:25600
	ds_read_b64_tr_b16 v[102:103], v156 offset:26112
	ds_read_b64_tr_b16 v[96:97], v156 offset:29696
	ds_read_b64_tr_b16 v[98:99], v156 offset:30208
	s_cbranch_scc1 .Latt_dma0
	s_add_i32 s6, s86, s63
	s_mov_b32 s7, m0
	s_mov_b32 m0, s6
	s_nop 0
	global_load_lds_dwordx4 v211, s[48:49]
	s_mov_b32 m0, s7
.Latt_dma0:
	s_waitcnt lgkmcnt(14)
	v_mfma_f32_32x32x16_bf16 v[48:63], v[216:219], v[144:147], v[48:63]
	s_andn2_b64 vcc, exec, s[50:51]
	s_waitcnt lgkmcnt(12)
	v_mfma_f32_32x32x16_bf16 v[32:47], v[216:219], v[140:143], v[32:47]
	s_waitcnt lgkmcnt(10)
	v_mfma_f32_32x32x16_bf16 v[16:31], v[216:219], v[136:139], v[16:31]
	s_waitcnt lgkmcnt(8)
	v_mfma_f32_32x32x16_bf16 v[0:15], v[216:219], v[132:135], v[0:15]
	v_cndmask_b32_e64 v132, 0, 1, s[50:51]
	v_cmp_ne_u32_e64 s[6:7], 1, v132
	v_mfma_f32_32x32x16_bf16 v[64:79], v[216:219], v[128:131], v[64:79]
.LBB0_1013:
	v_exp_f32_e32 v104, v104
	v_exp_f32_e32 v105, v105
	v_exp_f32_e32 v106, v106
	v_exp_f32_e32 v107, v107
	v_exp_f32_e32 v108, v108
	v_exp_f32_e32 v109, v109
	v_exp_f32_e32 v110, v110
	v_exp_f32_e32 v111, v111
	v_cvt_pk_bf16_f32 v140, v104, v105
	v_cvt_pk_bf16_f32 v141, v106, v107
	v_cvt_pk_bf16_f32 v142, v108, v109
	v_cvt_pk_bf16_f32 v143, v110, v111
	ds_read_b64_tr_b16 v[136:137], v156 offset:18432
	ds_read_b64_tr_b16 v[138:139], v156 offset:18944
	ds_read_b64_tr_b16 v[132:133], v156 offset:22528
	ds_read_b64_tr_b16 v[134:135], v156 offset:23040
	ds_read_b64_tr_b16 v[108:109], v156 offset:26624
	ds_read_b64_tr_b16 v[110:111], v156 offset:27136
	ds_read_b64_tr_b16 v[104:105], v156 offset:30720
	ds_read_b64_tr_b16 v[106:107], v156 offset:31232
	s_cbranch_vccnz .Latt_dma1
	s_add_u32 s50, s42, 0x80
	s_addc_u32 s51, s43, 0
	s_add_i32 s58, s86, s63
	s_addk_i32 s58, 0x2000
	s_mov_b32 s59, m0
	s_mov_b32 m0, s58
	s_nop 0
	global_load_lds_dwordx4 v211, s[50:51]
	s_mov_b32 m0, s59
.Latt_dma1:
	s_waitcnt lgkmcnt(14)
	v_mfma_f32_32x32x16_bf16 v[48:63], v[140:143], v[152:155], v[48:63]
	s_and_b64 vcc, exec, s[6:7]
	s_waitcnt lgkmcnt(12)
	v_mfma_f32_32x32x16_bf16 v[32:47], v[140:143], v[148:151], v[32:47]
	s_waitcnt lgkmcnt(10)
	v_mfma_f32_32x32x16_bf16 v[16:31], v[140:143], v[100:103], v[16:31]
	s_waitcnt lgkmcnt(8)
	v_mfma_f32_32x32x16_bf16 v[0:15], v[140:143], v[96:99], v[0:15]
	v_mfma_f32_32x32x16_bf16 v[64:79], v[140:143], v[128:131], v[64:79]
.LBB0_1015:
	v_exp_f32_e32 v80, v80
	v_exp_f32_e32 v81, v81
	v_exp_f32_e32 v82, v82
	v_exp_f32_e32 v83, v83
	v_exp_f32_e32 v84, v84
	v_exp_f32_e32 v85, v85
	v_exp_f32_e32 v86, v86
	v_exp_f32_e32 v87, v87
	v_cvt_pk_bf16_f32 v140, v80, v81
	v_cvt_pk_bf16_f32 v141, v82, v83
	v_cvt_pk_bf16_f32 v142, v84, v85
	v_cvt_pk_bf16_f32 v143, v86, v87
	ds_read_b64_tr_b16 v[100:101], v156 offset:19456
	ds_read_b64_tr_b16 v[102:103], v156 offset:19968
	ds_read_b64_tr_b16 v[96:97], v156 offset:23552
	ds_read_b64_tr_b16 v[98:99], v156 offset:24064
	ds_read_b64_tr_b16 v[84:85], v156 offset:27648
	ds_read_b64_tr_b16 v[86:87], v156 offset:28160
	ds_read_b64_tr_b16 v[80:81], v156 offset:31744
	ds_read_b64_tr_b16 v[82:83], v156 offset:32256
	s_cbranch_vccnz .Latt_dma2
	s_add_i32 s50, s86, s68
	s_mov_b32 s51, m0
	s_mov_b32 m0, s50
	s_nop 0
	global_load_lds_dwordx4 v212, s[40:41]
	s_mov_b32 m0, s51
.Latt_dma2:
	s_waitcnt lgkmcnt(14)
	v_mfma_f32_32x32x16_bf16 v[48:63], v[140:143], v[136:139], v[48:63]
	s_and_b64 vcc, exec, s[6:7]
	s_waitcnt lgkmcnt(12)
	v_mfma_f32_32x32x16_bf16 v[32:47], v[140:143], v[132:135], v[32:47]
	s_waitcnt lgkmcnt(10)
	v_mfma_f32_32x32x16_bf16 v[16:31], v[140:143], v[108:111], v[16:31]
	s_waitcnt lgkmcnt(8)
	v_mfma_f32_32x32x16_bf16 v[0:15], v[140:143], v[104:107], v[0:15]
	v_mfma_f32_32x32x16_bf16 v[64:79], v[140:143], v[128:131], v[64:79]
	s_cbranch_vccnz .LBB0_1004
	s_add_u32 s6, s42, 0x480
	s_addc_u32 s7, s43, 0
	s_add_i32 s50, s86, s68
	s_addk_i32 s50, 0x2000
	s_mov_b32 s51, m0
	s_mov_b32 m0, s50
	s_nop 0
	global_load_lds_dwordx4 v212, s[6:7]
	s_mov_b32 m0, s51
	s_branch .LBB0_1004
